# P0: layer-0 w_in conversion items handled by workgroups 160..255 (8 x-rows per wave) instead of 0..95 (9 rows for 0..63), grid 256 only
# speedup vs baseline: 1.0076x; 1.0027x over previous
; #define LAS __attribute__((address_space(3)))
; #define GPTR(T, p) gptr_<T>(p)
; __device__ __forceinline__ void p0_convert(const Args& args, LAS unsigned char* lds, int lane, int wave, int gw, int NGW, int it_lo, int it_hi) {
;     ...
;     for (int it = it_lo + gw; it < it_hi; it += 2 * NGW) {
;         TItem ta, tb2; f32x4 va[8], vb[8]; const bool two = it + NGW < it_hi;
;         item(it, ta); p0_t_load(ta, lane, va);
;         if (two) { item(it + NGW, tb2); p0_t_load(tb2, lane, vb); }
;         p0_t_finish(ta, lane, va, scr);
;         if (two) p0_t_finish(tb2, lane, vb, scr);
;     }
; }
; __device__ __forceinline__ void p0_prologue(const Args& args, LAS unsigned char* lds, int tid, int lane, int wave, int bx, int G) {
;     unsigned char* ws = GPTR(unsigned char, args.ws);
;     const int gw = bx * NWAVES + wave, NGW = G * NWAVES;
;     const int gt = bx * (NWAVES * 64) + tid, NGT = G * NWAVES * 64;
;     p0_convert(args, lds, lane, wave, gw, NGW, 0, P0_I_IN);
.LBB0_14:
	s_load_dwordx16 s[12:27], s[0:1], 0x40
	s_andn2_b64 vcc, exec, s[2:3]
	s_waitcnt lgkmcnt(0)
	v_writelane_b32 v252, s12, 47
	s_nop 1
	v_writelane_b32 v252, s13, 48
	v_writelane_b32 v252, s14, 49
	v_writelane_b32 v252, s15, 50
	v_writelane_b32 v252, s16, 51
	v_writelane_b32 v252, s17, 52
	v_writelane_b32 v252, s18, 53
	v_writelane_b32 v252, s19, 54
	v_writelane_b32 v252, s20, 55
	v_writelane_b32 v252, s21, 56
	v_writelane_b32 v252, s22, 57
	v_writelane_b32 v252, s23, 58
	v_writelane_b32 v252, s24, 59
	v_writelane_b32 v252, s25, 60
	v_writelane_b32 v252, s26, 61
	v_writelane_b32 v252, s27, 62
	s_cbranch_vccnz .LBB0_176
	s_lshr_b32 s4, s8, 6
	s_load_dwordx4 s[8:11], s[0:1], 0x100
	v_readlane_b32 s2, v252, 0
	s_lshl_b32 s2, s2, 3
	v_and_b32_e32 v1, 63, v0
	s_waitcnt lgkmcnt(0)
	s_mov_b64 s[14:15], s[10:11]
	s_mov_b64 s[12:13], s[8:9]
	s_mov_b64 s[12:13], s[14:15]
	s_add_i32 s8, s4, s2
	s_load_dword s2, s[0:1], 0x120
	s_waitcnt lgkmcnt(0)
	s_lshl_b32 s10, s2, 3
	s_mov_b64 s[2:3], s[14:15]
	s_mov_b32 s29, s8
	s_cmpk_lg_i32 s10, 0x800
	s_cbranch_scc1 .Lp0_keep
	s_add_i32 s29, s8, 0xfffffb00
	s_cmpk_lt_i32 s29, 0
	s_cselect_b32 s29, 0x7000, s29
.Lp0_keep:
	s_cmpk_gt_i32 s29, 0x2ff
	s_cbranch_scc1 .LBB0_54
	s_lshl_b32 s4, s4, 14
	s_add_i32 s4, s4, 0
	s_add_u32 s9, s2, 0x100000
	s_load_dword s2, s[0:1], 0x120
	v_lshlrev_b32_e32 v2, 2, v0
	v_lshlrev_b32_e32 v4, 3, v0
	v_lshrrev_b32_e32 v70, 3, v1
	v_and_b32_e32 v2, 28, v2
	v_and_b32_e32 v4, 56, v4
	v_mov_b32_e32 v73, 0
	v_lshl_add_u32 v3, v2, 2, s4
	v_mul_u32_u24_e32 v5, 0x84, v70
	v_mul_u32_u24_e32 v6, 0x84, v4
	v_lshlrev_b32_e32 v7, 2, v70
	v_lshlrev_b32_e32 v74, 2, v2
	s_addc_u32 s11, s3, 0
	v_or_b32_e32 v82, 8, v70
	v_or_b32_e32 v83, 16, v70
	v_or_b32_e32 v84, 24, v70
	v_or_b32_e32 v85, 32, v70
	v_or_b32_e32 v86, 40, v70
	v_or_b32_e32 v87, 48, v70
	v_or_b32_e32 v88, 56, v70
	v_add3_u32 v89, s4, v6, v7
	s_waitcnt lgkmcnt(0)
	s_lshl_b32 s28, s2, 4
	v_mov_b32_e32 v71, v73
	v_mov_b32_e32 v76, v74
	v_mov_b32_e32 v77, v73
	v_lshlrev_b32_e32 v72, 1, v4
	v_add_u32_e32 v90, v3, v5
	s_branch .LBB0_19
